# W_up epilogue: ssq row sums precomputed by the leading half into LDS (8 serialized load round trips removed)
# speedup vs baseline: 1.0273x; 1.0160x over previous
.LBB0_1797:
	s_xor_b64 s[90:91], s[88:89], -1
	s_and_b64 vcc, exec, s[34:35]
	s_cbranch_vccz .LBB0_1799
	v_mbcnt_lo_u32_b32 v164, -1, 0
	v_mbcnt_hi_u32_b32 v164, -1, v164
	v_readlane_b32 s100, v255, 4
	v_and_b32_e32 v165, 48, v164
	v_lshlrev_b32_e32 v165, 1, v165
	s_and_b32 s100, s100, 3
	s_lshl_b32 s100, s100, 6
	v_add_u32_e32 v164, s100, v164
	v_lshl_add_u32 v166, s16, 8, v164
	v_lshlrev_b32_e32 v166, 7, v166
	v_sub_u32_e32 v166, v166, v165
	v_ashrrev_i32_e32 v167, 31, v166
	v_lshl_add_u64 v[168:169], v[180:181], 0, v[166:167]
	global_load_dwordx4 v[132:135], v[168:169], off
	global_load_dwordx4 v[136:139], v[168:169], off offset:16
	global_load_dwordx4 v[140:143], v[168:169], off offset:32
	global_load_dwordx4 v[144:147], v[168:169], off offset:48
	global_load_dwordx4 v[148:151], v[168:169], off offset:64
	global_load_dwordx4 v[152:155], v[168:169], off offset:80
	global_load_dwordx4 v[156:159], v[168:169], off offset:96
	global_load_dwordx4 v[160:163], v[168:169], off offset:112
	v_lshlrev_b32_e32 v164, 4, v164
	v_add_u32_e32 v164, 0x20800, v164
	s_waitcnt vmcnt(0)
	v_add_f32_e32 v132, v132, v133
	v_add_f32_e32 v134, v134, v135
	v_add_f32_e32 v132, v132, v134
	v_add_f32_e32 v136, v136, v137
	v_add_f32_e32 v138, v138, v139
	v_add_f32_e32 v136, v136, v138
	v_add_f32_e32 v188, v132, v136
	v_add_f32_e32 v140, v140, v141
	v_add_f32_e32 v142, v142, v143
	v_add_f32_e32 v140, v140, v142
	v_add_f32_e32 v144, v144, v145
	v_add_f32_e32 v146, v146, v147
	v_add_f32_e32 v144, v144, v146
	v_add_f32_e32 v189, v140, v144
	v_add_f32_e32 v148, v148, v149
	v_add_f32_e32 v150, v150, v151
	v_add_f32_e32 v148, v148, v150
	v_add_f32_e32 v152, v152, v153
	v_add_f32_e32 v154, v154, v155
	v_add_f32_e32 v152, v152, v154
	v_add_f32_e32 v190, v148, v152
	v_add_f32_e32 v156, v156, v157
	v_add_f32_e32 v158, v158, v159
	v_add_f32_e32 v156, v156, v158
	v_add_f32_e32 v160, v160, v161
	v_add_f32_e32 v162, v162, v163
	v_add_f32_e32 v160, v160, v162
	v_add_f32_e32 v191, v156, v160
	ds_write_b128 v164, v[188:191]
	s_waitcnt lgkmcnt(0)
	s_barrier
.LBB0_1799:
	v_mbcnt_lo_u32_b32 v223, -1, 0
	v_mbcnt_hi_u32_b32 v223, -1, v223
	v_lshrrev_b32_e32 v223, 2, v223
	v_and_b32_e32 v223, 12, v223
	v_lshl_add_u32 v222, v214, 4, v223
	v_add_u32_e32 v222, 0x20800, v222
	v_lshl_or_b32 v98, s14, 7, v235
	v_lshl_add_u32 v212, s16, 8, v214
	v_ashrrev_i32_e32 v99, 31, v98
	v_ashrrev_i32_e32 v213, 31, v212
	v_lshlrev_b64 v[132:133], 2, v[98:99]
	s_mov_b32 s6, -1
	v_lshl_add_u64 v[136:137], s[56:57], 0, v[132:133]
	v_lshl_add_u64 v[140:141], s[62:63], 0, v[132:133]
	v_lshl_add_u64 v[144:145], s[64:65], 0, v[132:133]
	v_lshl_add_u64 v[160:161], s[58:59], 0, v[132:133]
	global_load_dwordx4 v[132:135], v[136:137], off offset:16
	global_load_dwordx4 v[148:151], v[136:137], off
	s_nop 0
	global_load_dwordx4 v[136:139], v[140:141], off offset:16
	global_load_dwordx4 v[152:155], v[140:141], off
	s_nop 0
	global_load_dwordx4 v[140:143], v[144:145], off offset:16
	global_load_dwordx4 v[156:159], v[144:145], off
	s_nop 0
	global_load_dwordx4 v[144:147], v[160:161], off offset:16
	s_nop 0
	global_load_dwordx4 v[160:163], v[160:161], off
	s_nop 0
	v_or_b32_e32 v206, 16, v212
	v_ashrrev_i32_e32 v207, 31, v206
	v_cmp_lt_i32_e32 vcc, v216, v252
	s_mov_b32 s6, 0x3a000000
	v_or_b32_e32 v204, 32, v212
	v_cndmask_b32_e32 v96, v217, v216, vcc
	v_lshlrev_b32_e32 v199, 2, v96
	v_cmp_lt_i32_e32 vcc, v218, v252
	v_ashrrev_i32_e32 v205, 31, v204
	v_or_b32_e32 v194, 48, v212
	v_cndmask_b32_e32 v96, v217, v218, vcc
	v_lshlrev_b32_e32 v198, 2, v96
	v_ashrrev_i32_e32 v195, 31, v194
	v_add_u32_e32 v192, 0x80, v212
	v_ashrrev_i32_e32 v193, 31, v192
	v_add_u32_e32 v190, 0x90, v212
	v_ashrrev_i32_e32 v191, 31, v190
	s_mov_b32 s10, 0xfe03f81
	ds_read_b32 v165, v222
	ds_read_b32 v164, v222 offset:256
	s_waitcnt lgkmcnt(0)
	ds_bpermute_b32 v167, v199, v165
	ds_bpermute_b32 v166, v199, v164
	s_waitcnt lgkmcnt(0)
	v_pk_add_f32 v[164:165], v[164:165], v[166:167]
	ds_bpermute_b32 v167, v198, v165
	ds_bpermute_b32 v166, v198, v164
	s_waitcnt lgkmcnt(0)
	v_pk_add_f32 v[164:165], v[164:165], v[166:167]
	s_nop 0
	v_pk_fma_f32 v[224:225], v[164:165], s[6:7], v[242:243] op_sel_hi:[1,0,0]
	s_nop 0
	v_mul_f32_e32 v96, 0x4b800000, v225
	v_cmp_gt_f32_e32 vcc, s45, v225
	v_cmp_gt_f32_e64 s[6:7], s45, v224
	s_nop 0
	v_cndmask_b32_e32 v96, v225, v96, vcc
	v_rsq_f32_e32 v96, v96
	s_nop 0
	v_mul_f32_e32 v164, 0x45800000, v96
	v_cndmask_b32_e32 v96, v96, v164, vcc
	v_pk_mul_f32 v[226:227], v[94:95], v[96:97] op_sel_hi:[1,0]
	v_pk_mul_f32 v[228:229], v[88:89], v[96:97] op_sel_hi:[1,0]
	v_pk_mul_f32 v[230:231], v[90:91], v[96:97] op_sel_hi:[1,0]
	ds_read_b32 v165, v222 offset:512
	ds_read_b32 v164, v222 offset:768
	s_waitcnt lgkmcnt(0)
	ds_bpermute_b32 v167, v199, v165
	ds_bpermute_b32 v166, v199, v164
	s_waitcnt lgkmcnt(0)
	v_pk_add_f32 v[208:209], v[164:165], v[166:167]
	ds_bpermute_b32 v211, v198, v209
	ds_bpermute_b32 v210, v198, v208
	v_add_u32_e32 v188, 0xa0, v212
	ds_read_b32 v165, v222 offset:2048
	ds_read_b32 v164, v222 offset:2304
	s_waitcnt lgkmcnt(0)
	ds_bpermute_b32 v167, v199, v165
	ds_bpermute_b32 v166, v199, v164
	v_ashrrev_i32_e32 v189, 31, v188
	s_waitcnt lgkmcnt(0)
	v_pk_add_f32 v[200:201], v[164:165], v[166:167]
	ds_bpermute_b32 v203, v198, v201
	ds_bpermute_b32 v202, v198, v200
	v_add_u32_e32 v186, 0xb0, v212
	v_ashrrev_i32_e32 v187, 31, v186
	v_pk_mul_f32 v[168:169], v[128:129], v[96:97] op_sel_hi:[1,0]
	ds_read_b32 v165, v222 offset:2560
	ds_read_b32 v164, v222 offset:2816
	s_waitcnt lgkmcnt(0)
	ds_bpermute_b32 v167, v199, v165
	ds_bpermute_b32 v166, v199, v164
	v_pk_mul_f32 v[222:223], v[92:93], v[96:97] op_sel_hi:[1,0]
	v_pk_mul_f32 v[170:171], v[130:131], v[96:97] op_sel_hi:[1,0]
	s_waitcnt lgkmcnt(0)
	v_pk_add_f32 v[196:197], v[164:165], v[166:167]
	s_waitcnt vmcnt(0)
	v_mov_b32_dpp v164, v168 row_shr:2 row_mask:0xf bank_mask:0xf bound_ctrl:1
	v_mov_b32_dpp v165, v169 row_shr:2 row_mask:0xf bank_mask:0xf bound_ctrl:1
	v_mov_b32_dpp v166, v168 row_shr:1 row_mask:0xf bank_mask:0xf bound_ctrl:1
	v_mov_b32_dpp v167, v169 row_shr:1 row_mask:0xf bank_mask:0xf bound_ctrl:1
	v_cndmask_b32_e64 v165, v165, 0, s[4:5]
	v_cndmask_b32_e64 v164, v164, 0, s[4:5]
	v_pk_fma_f32 v[164:165], v[148:149], v[164:165], v[160:161]
	v_cndmask_b32_e64 v167, v167, 0, s[2:3]
	v_cndmask_b32_e64 v166, v166, 0, s[2:3]
	v_pk_fma_f32 v[164:165], v[152:153], v[166:167], v[164:165]
	ds_bpermute_b32 v199, v198, v197
	v_pk_fma_f32 v[164:165], v[156:157], v[168:169], v[164:165]
	ds_bpermute_b32 v198, v198, v196
	v_mul_f32_e32 v166, 0x3d372713, v164
	v_mul_f32_e32 v167, 0x3d372713, v165
	v_mul_f32_e32 v166, v164, v166
	v_mul_f32_e32 v167, v165, v167
	v_fma_f32 v166, v164, v166, v164
	v_fma_f32 v167, v165, v167, v165
	v_mul_f32_e32 v166, 0xbfcc422a, v166
	v_mul_f32_e32 v167, 0xbfcc422a, v167
	v_mul_f32_e32 v166, 0x3fb8aa3b, v166
	v_mul_f32_e32 v167, 0x3fb8aa3b, v167
	v_exp_f32_e32 v166, v166
	v_exp_f32_e32 v167, v167
	v_add_f32_e32 v166, 1.0, v166
	v_add_f32_e32 v167, 1.0, v167
	v_rcp_f32_e32 v166, v166
	v_rcp_f32_e32 v167, v167
	s_nop 0
	v_pk_mul_f32 v[164:165], v[164:165], v[166:167]
	s_nop 0
	v_pk_mul_f32 v[232:233], v[222:223], v[164:165]
	v_mov_b32_dpp v164, v170 row_shr:2 row_mask:0xf bank_mask:0xf bound_ctrl:1
	v_mov_b32_dpp v165, v171 row_shr:2 row_mask:0xf bank_mask:0xf bound_ctrl:1
	v_mov_b32_dpp v166, v170 row_shr:1 row_mask:0xf bank_mask:0xf bound_ctrl:1
	v_mov_b32_dpp v167, v171 row_shr:1 row_mask:0xf bank_mask:0xf bound_ctrl:1
	v_cndmask_b32_e64 v165, v165, 0, s[4:5]
	v_cndmask_b32_e64 v164, v164, 0, s[4:5]
	v_pk_fma_f32 v[164:165], v[150:151], v[164:165], v[162:163]
	v_cndmask_b32_e64 v167, v167, 0, s[2:3]
	v_cndmask_b32_e64 v166, v166, 0, s[2:3]
	v_pk_fma_f32 v[164:165], v[154:155], v[166:167], v[164:165]
	s_nop 0
	v_pk_fma_f32 v[164:165], v[158:159], v[170:171], v[164:165]
	s_nop 0
	v_mul_f32_e32 v166, 0x3d372713, v164
	v_mul_f32_e32 v167, 0x3d372713, v165
	v_mul_f32_e32 v166, v164, v166
	v_mul_f32_e32 v167, v165, v167
	v_fma_f32 v166, v164, v166, v164
	v_fma_f32 v167, v165, v167, v165
	v_mul_f32_e32 v166, 0xbfcc422a, v166
	v_mul_f32_e32 v167, 0xbfcc422a, v167
	v_mul_f32_e32 v166, 0x3fb8aa3b, v166
	v_mul_f32_e32 v167, 0x3fb8aa3b, v167
	v_exp_f32_e32 v166, v166
	v_exp_f32_e32 v167, v167
	v_add_f32_e32 v166, 1.0, v166
	v_add_f32_e32 v167, 1.0, v167
	v_rcp_f32_e32 v166, v166
	v_rcp_f32_e32 v167, v167
	s_nop 0
	v_pk_mul_f32 v[164:165], v[164:165], v[166:167]
	s_nop 0
	v_pk_mul_f32 v[240:241], v[226:227], v[164:165]
	v_pk_mul_f32 v[164:165], v[124:125], v[96:97] op_sel_hi:[1,0]
	s_nop 1
	v_mov_b32_dpp v166, v164 row_shr:2 row_mask:0xf bank_mask:0xf bound_ctrl:1
	v_mov_b32_dpp v167, v165 row_shr:2 row_mask:0xf bank_mask:0xf bound_ctrl:1
	v_mov_b32_dpp v187, v164 row_shr:1 row_mask:0xf bank_mask:0xf bound_ctrl:1
	v_mov_b32_dpp v189, v165 row_shr:1 row_mask:0xf bank_mask:0xf bound_ctrl:1
	v_cndmask_b32_e64 v167, v167, 0, s[4:5]
	v_cndmask_b32_e64 v166, v166, 0, s[4:5]
	v_pk_fma_f32 v[166:167], v[132:133], v[166:167], v[144:145]
	v_cndmask_b32_e64 v239, v189, 0, s[2:3]
	v_cndmask_b32_e64 v238, v187, 0, s[2:3]
	v_pk_fma_f32 v[166:167], v[136:137], v[238:239], v[166:167]
	s_nop 0
	v_pk_fma_f32 v[166:167], v[140:141], v[164:165], v[166:167]
	s_nop 0
	v_mul_f32_e32 v187, 0x3d372713, v166
	v_mul_f32_e32 v187, v166, v187
	v_fma_f32 v187, v166, v187, v166
	v_mul_f32_e32 v187, 0xbfcc422a, v187
	v_mul_f32_e32 v187, 0x3fb8aa3b, v187
	v_exp_f32_e32 v187, v187
	s_nop 0
	v_add_f32_e32 v187, 1.0, v187
	v_rcp_f32_e32 v238, v187
	v_mul_f32_e32 v187, 0x3d372713, v167
	v_mul_f32_e32 v187, v167, v187
	v_fma_f32 v187, v167, v187, v167
	v_mul_f32_e32 v187, 0xbfcc422a, v187
	v_mul_f32_e32 v187, 0x3fb8aa3b, v187
	v_exp_f32_e32 v187, v187
	s_nop 0
	v_add_f32_e32 v187, 1.0, v187
	v_rcp_f32_e32 v239, v187
	s_nop 0
	v_pk_mul_f32 v[166:167], v[166:167], v[238:239]
	s_nop 0
	v_pk_mul_f32 v[242:243], v[228:229], v[166:167]
	v_pk_mul_f32 v[166:167], v[126:127], v[96:97] op_sel_hi:[1,0]
	s_nop 1
	v_mov_b32_dpp v187, v166 row_shr:2 row_mask:0xf bank_mask:0xf bound_ctrl:1
	v_mov_b32_dpp v191, v167 row_shr:2 row_mask:0xf bank_mask:0xf bound_ctrl:1
	v_mov_b32_dpp v96, v166 row_shr:1 row_mask:0xf bank_mask:0xf bound_ctrl:1
	v_mov_b32_dpp v189, v167 row_shr:1 row_mask:0xf bank_mask:0xf bound_ctrl:1
	v_cndmask_b32_e64 v245, v191, 0, s[4:5]
	v_cndmask_b32_e64 v244, v187, 0, s[4:5]
	v_cndmask_b32_e64 v239, v189, 0, s[2:3]
	v_cndmask_b32_e64 v238, v96, 0, s[2:3]
	v_pk_fma_f32 v[244:245], v[134:135], v[244:245], v[146:147]
	s_nop 0
	v_pk_fma_f32 v[238:239], v[138:139], v[238:239], v[244:245]
	s_nop 0
	v_pk_fma_f32 v[238:239], v[142:143], v[166:167], v[238:239]
	s_nop 0
	v_mul_f32_e32 v96, 0x3d372713, v238
	v_mul_f32_e32 v96, v238, v96
	v_fma_f32 v96, v238, v96, v238
	v_mul_f32_e32 v96, 0xbfcc422a, v96
	v_mul_f32_e32 v96, 0x3fb8aa3b, v96
	v_exp_f32_e32 v96, v96
	s_nop 0
	v_add_f32_e32 v96, 1.0, v96
	v_rcp_f32_e32 v244, v96
	v_mul_f32_e32 v96, 0x3d372713, v239
	v_mul_f32_e32 v96, v239, v96
	v_fma_f32 v96, v239, v96, v239
	v_mul_f32_e32 v96, 0xbfcc422a, v96
	v_mul_f32_e32 v96, 0x3fb8aa3b, v96
	v_exp_f32_e32 v96, v96
	s_nop 0
	v_add_f32_e32 v96, 1.0, v96
	v_rcp_f32_e32 v245, v96
	v_mul_hi_i32 v96, v212, s10
	v_lshrrev_b32_e32 v187, 31, v96
	v_ashrrev_i32_e32 v96, 7, v96
	v_pk_mul_f32 v[238:239], v[238:239], v[244:245]
	s_movk_i32 s10, 0x203d
	v_pk_mul_f32 v[244:245], v[230:231], v[238:239]
	v_cvt_pk_bf16_f32 v238, v232, v233
	v_mov_b64_e32 v[232:233], s[24:25]
	v_mad_i64_i32 v[232:233], s[8:9], v212, s43, v[232:233]
	v_cvt_pk_bf16_f32 v239, v240, v241
	v_cvt_pk_bf16_f32 v240, v242, v243
	v_cvt_pk_bf16_f32 v241, v244, v245
	v_lshl_add_u64 v[232:233], v[98:99], 1, v[232:233]
	global_store_dwordx4 v[232:233], v[238:241], off
	v_add_u32_e32 v232, v96, v187
	v_mul_i32_i24_e32 v96, 0x810, v232
	v_cmp_gt_i32_e64 s[8:9], s73, v212
	v_sub_u32_e32 v96, v212, v96
	v_cmp_lt_i32_e32 vcc, s10, v212
	v_cndmask_b32_e64 v187, 0, v96, s[8:9]
	v_cmp_gt_i32_e64 s[10:11], 2, v187
	s_or_b64 s[10:11], vcc, s[10:11]
	s_or_b64 s[78:79], s[4:5], s[10:11]
	s_and_saveexec_b64 s[10:11], s[78:79]
	s_cbranch_execz .LBB0_1801
	v_mad_i64_i32 v[212:213], s[78:79], v212, s43, 0
	v_lshl_add_u64 v[212:213], v[212:213], 1, s[22:23]
	v_cvt_pk_bf16_f32 v238, v168, v169
	v_cvt_pk_bf16_f32 v239, v170, v171
	v_cvt_pk_bf16_f32 v240, v164, v165
	v_cvt_pk_bf16_f32 v241, v166, v167
	v_lshl_add_u64 v[212:213], v[98:99], 1, v[212:213]
	global_store_dwordx4 v[212:213], v[238:241], off
	v_add_co_u32_e32 v212, vcc, 0x2000, v212
	v_cvt_pk_bf16_f32 v242, v222, v223
	v_cvt_pk_bf16_f32 v243, v226, v227
	v_cvt_pk_bf16_f32 v244, v228, v229
	v_cvt_pk_bf16_f32 v245, v230, v231
	v_addc_co_u32_e32 v213, vcc, 0, v213, vcc
	global_store_dwordx4 v[212:213], v[242:245], off offset:2816

.LBB0_1914:
	s_xor_b64 s[86:87], s[66:67], -1
	s_and_b64 vcc, exec, s[30:31]
	s_cbranch_vccz .LBB0_1916
	v_mbcnt_lo_u32_b32 v164, -1, 0
	v_mbcnt_hi_u32_b32 v164, -1, v164
	v_readlane_b32 s100, v255, 4
	v_and_b32_e32 v165, 48, v164
	v_lshlrev_b32_e32 v165, 1, v165
	s_and_b32 s100, s100, 3
	s_lshl_b32 s100, s100, 6
	v_add_u32_e32 v164, s100, v164
	v_lshl_add_u32 v166, s14, 8, v164
	v_lshlrev_b32_e32 v166, 7, v166
	v_sub_u32_e32 v166, v166, v165
	v_ashrrev_i32_e32 v167, 31, v166
	v_lshl_add_u64 v[168:169], v[180:181], 0, v[166:167]
	global_load_dwordx4 v[132:135], v[168:169], off
	global_load_dwordx4 v[136:139], v[168:169], off offset:16
	global_load_dwordx4 v[140:143], v[168:169], off offset:32
	global_load_dwordx4 v[144:147], v[168:169], off offset:48
	global_load_dwordx4 v[148:151], v[168:169], off offset:64
	global_load_dwordx4 v[152:155], v[168:169], off offset:80
	global_load_dwordx4 v[156:159], v[168:169], off offset:96
	global_load_dwordx4 v[160:163], v[168:169], off offset:112
	v_lshlrev_b32_e32 v164, 4, v164
	v_add_u32_e32 v164, 0x20800, v164
	s_waitcnt vmcnt(0)
	v_add_f32_e32 v132, v132, v133
	v_add_f32_e32 v134, v134, v135
	v_add_f32_e32 v132, v132, v134
	v_add_f32_e32 v136, v136, v137
	v_add_f32_e32 v138, v138, v139
	v_add_f32_e32 v136, v136, v138
	v_add_f32_e32 v188, v132, v136
	v_add_f32_e32 v140, v140, v141
	v_add_f32_e32 v142, v142, v143
	v_add_f32_e32 v140, v140, v142
	v_add_f32_e32 v144, v144, v145
	v_add_f32_e32 v146, v146, v147
	v_add_f32_e32 v144, v144, v146
	v_add_f32_e32 v189, v140, v144
	v_add_f32_e32 v148, v148, v149
	v_add_f32_e32 v150, v150, v151
	v_add_f32_e32 v148, v148, v150
	v_add_f32_e32 v152, v152, v153
	v_add_f32_e32 v154, v154, v155
	v_add_f32_e32 v152, v152, v154
	v_add_f32_e32 v190, v148, v152
	v_add_f32_e32 v156, v156, v157
	v_add_f32_e32 v158, v158, v159
	v_add_f32_e32 v156, v156, v158
	v_add_f32_e32 v160, v160, v161
	v_add_f32_e32 v162, v162, v163
	v_add_f32_e32 v160, v160, v162
	v_add_f32_e32 v191, v156, v160
	ds_write_b128 v164, v[188:191]
	s_waitcnt lgkmcnt(0)
	s_barrier
.LBB0_1916:
	v_mbcnt_lo_u32_b32 v223, -1, 0
	v_mbcnt_hi_u32_b32 v223, -1, v223
	v_lshrrev_b32_e32 v223, 2, v223
	v_and_b32_e32 v223, 12, v223
	v_lshl_add_u32 v222, v214, 4, v223
	v_add_u32_e32 v222, 0x20800, v222
	v_lshl_or_b32 v98, s12, 7, v235
	v_lshl_add_u32 v212, s14, 8, v214
	v_ashrrev_i32_e32 v99, 31, v98
	v_ashrrev_i32_e32 v213, 31, v212
	v_lshlrev_b64 v[132:133], 2, v[98:99]
	s_mov_b32 s6, -1
	v_lshl_add_u64 v[136:137], s[56:57], 0, v[132:133]
	v_lshl_add_u64 v[140:141], s[34:35], 0, v[132:133]
	v_lshl_add_u64 v[144:145], s[60:61], 0, v[132:133]
	v_lshl_add_u64 v[160:161], s[58:59], 0, v[132:133]
	global_load_dwordx4 v[132:135], v[136:137], off offset:16
	global_load_dwordx4 v[148:151], v[136:137], off
	s_nop 0
	global_load_dwordx4 v[136:139], v[140:141], off offset:16
	global_load_dwordx4 v[152:155], v[140:141], off
	s_nop 0
	global_load_dwordx4 v[140:143], v[144:145], off offset:16
	global_load_dwordx4 v[156:159], v[144:145], off
	s_nop 0
	global_load_dwordx4 v[144:147], v[160:161], off offset:16
	s_nop 0
	global_load_dwordx4 v[160:163], v[160:161], off
	s_nop 0
	v_or_b32_e32 v206, 16, v212
	v_ashrrev_i32_e32 v207, 31, v206
	v_cmp_lt_i32_e32 vcc, v216, v252
	s_mov_b32 s6, 0x3a000000
	v_or_b32_e32 v204, 32, v212
	v_cndmask_b32_e32 v96, v217, v216, vcc
	v_lshlrev_b32_e32 v199, 2, v96
	v_cmp_lt_i32_e32 vcc, v218, v252
	v_ashrrev_i32_e32 v205, 31, v204
	v_or_b32_e32 v194, 48, v212
	v_cndmask_b32_e32 v96, v217, v218, vcc
	v_lshlrev_b32_e32 v198, 2, v96
	v_ashrrev_i32_e32 v195, 31, v194
	v_add_u32_e32 v192, 0x80, v212
	v_ashrrev_i32_e32 v193, 31, v192
	v_add_u32_e32 v190, 0x90, v212
	v_ashrrev_i32_e32 v191, 31, v190
	s_mov_b32 s10, 0xfe03f81
	ds_read_b32 v165, v222
	ds_read_b32 v164, v222 offset:256
	s_waitcnt lgkmcnt(0)
	ds_bpermute_b32 v167, v199, v165
	ds_bpermute_b32 v166, v199, v164
	s_waitcnt lgkmcnt(0)
	v_pk_add_f32 v[164:165], v[164:165], v[166:167]
	ds_bpermute_b32 v167, v198, v165
	ds_bpermute_b32 v166, v198, v164
	s_waitcnt lgkmcnt(0)
	v_pk_add_f32 v[164:165], v[164:165], v[166:167]
	s_nop 0
	v_pk_fma_f32 v[224:225], v[164:165], s[6:7], v[242:243] op_sel_hi:[1,0,0]
	s_nop 0
	v_mul_f32_e32 v96, 0x4b800000, v225
	v_cmp_gt_f32_e32 vcc, s45, v225
	v_cmp_gt_f32_e64 s[6:7], s45, v224
	s_nop 0
	v_cndmask_b32_e32 v96, v225, v96, vcc
	v_rsq_f32_e32 v96, v96
	s_nop 0
	v_mul_f32_e32 v164, 0x45800000, v96
	v_cndmask_b32_e32 v96, v96, v164, vcc
	v_pk_mul_f32 v[226:227], v[94:95], v[96:97] op_sel_hi:[1,0]
	v_pk_mul_f32 v[228:229], v[88:89], v[96:97] op_sel_hi:[1,0]
	v_pk_mul_f32 v[230:231], v[90:91], v[96:97] op_sel_hi:[1,0]
	ds_read_b32 v165, v222 offset:512
	ds_read_b32 v164, v222 offset:768
	s_waitcnt lgkmcnt(0)
	ds_bpermute_b32 v167, v199, v165
	ds_bpermute_b32 v166, v199, v164
	s_waitcnt lgkmcnt(0)
	v_pk_add_f32 v[208:209], v[164:165], v[166:167]
	ds_bpermute_b32 v211, v198, v209
	ds_bpermute_b32 v210, v198, v208
	v_add_u32_e32 v188, 0xa0, v212
	ds_read_b32 v165, v222 offset:2048
	ds_read_b32 v164, v222 offset:2304
	s_waitcnt lgkmcnt(0)
	ds_bpermute_b32 v167, v199, v165
	ds_bpermute_b32 v166, v199, v164
	v_ashrrev_i32_e32 v189, 31, v188
	s_waitcnt lgkmcnt(0)
	v_pk_add_f32 v[200:201], v[164:165], v[166:167]
	ds_bpermute_b32 v203, v198, v201
	ds_bpermute_b32 v202, v198, v200
	v_add_u32_e32 v186, 0xb0, v212
	v_ashrrev_i32_e32 v187, 31, v186
	v_pk_mul_f32 v[168:169], v[128:129], v[96:97] op_sel_hi:[1,0]
	ds_read_b32 v165, v222 offset:2560
	ds_read_b32 v164, v222 offset:2816
	s_waitcnt lgkmcnt(0)
	ds_bpermute_b32 v167, v199, v165
	ds_bpermute_b32 v166, v199, v164
	v_pk_mul_f32 v[222:223], v[92:93], v[96:97] op_sel_hi:[1,0]
	v_pk_mul_f32 v[170:171], v[130:131], v[96:97] op_sel_hi:[1,0]
	s_waitcnt lgkmcnt(0)
	v_pk_add_f32 v[196:197], v[164:165], v[166:167]
	s_waitcnt vmcnt(0)
	v_mov_b32_dpp v164, v168 row_shr:2 row_mask:0xf bank_mask:0xf bound_ctrl:1
	v_mov_b32_dpp v165, v169 row_shr:2 row_mask:0xf bank_mask:0xf bound_ctrl:1
	v_mov_b32_dpp v166, v168 row_shr:1 row_mask:0xf bank_mask:0xf bound_ctrl:1
	v_mov_b32_dpp v167, v169 row_shr:1 row_mask:0xf bank_mask:0xf bound_ctrl:1
	v_cndmask_b32_e64 v165, v165, 0, s[4:5]
	v_cndmask_b32_e64 v164, v164, 0, s[4:5]
	v_pk_fma_f32 v[164:165], v[148:149], v[164:165], v[160:161]
	v_cndmask_b32_e64 v167, v167, 0, s[2:3]
	v_cndmask_b32_e64 v166, v166, 0, s[2:3]
	v_pk_fma_f32 v[164:165], v[152:153], v[166:167], v[164:165]
	ds_bpermute_b32 v199, v198, v197
	v_pk_fma_f32 v[164:165], v[156:157], v[168:169], v[164:165]
	ds_bpermute_b32 v198, v198, v196
	v_mul_f32_e32 v166, 0x3d372713, v164
	v_mul_f32_e32 v167, 0x3d372713, v165
	v_mul_f32_e32 v166, v164, v166
	v_mul_f32_e32 v167, v165, v167
	v_fma_f32 v166, v164, v166, v164
	v_fma_f32 v167, v165, v167, v165
	v_mul_f32_e32 v166, 0xbfcc422a, v166
	v_mul_f32_e32 v167, 0xbfcc422a, v167
	v_mul_f32_e32 v166, 0x3fb8aa3b, v166
	v_mul_f32_e32 v167, 0x3fb8aa3b, v167
	v_exp_f32_e32 v166, v166
	v_exp_f32_e32 v167, v167
	v_add_f32_e32 v166, 1.0, v166
	v_add_f32_e32 v167, 1.0, v167
	v_rcp_f32_e32 v166, v166
	v_rcp_f32_e32 v167, v167
	s_nop 0
	v_pk_mul_f32 v[164:165], v[164:165], v[166:167]
	s_nop 0
	v_pk_mul_f32 v[232:233], v[222:223], v[164:165]
	v_mov_b32_dpp v164, v170 row_shr:2 row_mask:0xf bank_mask:0xf bound_ctrl:1
	v_mov_b32_dpp v165, v171 row_shr:2 row_mask:0xf bank_mask:0xf bound_ctrl:1
	v_mov_b32_dpp v166, v170 row_shr:1 row_mask:0xf bank_mask:0xf bound_ctrl:1
	v_mov_b32_dpp v167, v171 row_shr:1 row_mask:0xf bank_mask:0xf bound_ctrl:1
	v_cndmask_b32_e64 v165, v165, 0, s[4:5]
	v_cndmask_b32_e64 v164, v164, 0, s[4:5]
	v_pk_fma_f32 v[164:165], v[150:151], v[164:165], v[162:163]
	v_cndmask_b32_e64 v167, v167, 0, s[2:3]
	v_cndmask_b32_e64 v166, v166, 0, s[2:3]
	v_pk_fma_f32 v[164:165], v[154:155], v[166:167], v[164:165]
	s_nop 0
	v_pk_fma_f32 v[164:165], v[158:159], v[170:171], v[164:165]
	s_nop 0
	v_mul_f32_e32 v166, 0x3d372713, v164
	v_mul_f32_e32 v167, 0x3d372713, v165
	v_mul_f32_e32 v166, v164, v166
	v_mul_f32_e32 v167, v165, v167
	v_fma_f32 v166, v164, v166, v164
	v_fma_f32 v167, v165, v167, v165
	v_mul_f32_e32 v166, 0xbfcc422a, v166
	v_mul_f32_e32 v167, 0xbfcc422a, v167
	v_mul_f32_e32 v166, 0x3fb8aa3b, v166
	v_mul_f32_e32 v167, 0x3fb8aa3b, v167
	v_exp_f32_e32 v166, v166
	v_exp_f32_e32 v167, v167
	v_add_f32_e32 v166, 1.0, v166
	v_add_f32_e32 v167, 1.0, v167
	v_rcp_f32_e32 v166, v166
	v_rcp_f32_e32 v167, v167
	s_nop 0
	v_pk_mul_f32 v[164:165], v[164:165], v[166:167]
	s_nop 0
	v_pk_mul_f32 v[240:241], v[226:227], v[164:165]
	v_pk_mul_f32 v[164:165], v[124:125], v[96:97] op_sel_hi:[1,0]
	s_nop 1
	v_mov_b32_dpp v166, v164 row_shr:2 row_mask:0xf bank_mask:0xf bound_ctrl:1
	v_mov_b32_dpp v167, v165 row_shr:2 row_mask:0xf bank_mask:0xf bound_ctrl:1
	v_mov_b32_dpp v187, v164 row_shr:1 row_mask:0xf bank_mask:0xf bound_ctrl:1
	v_mov_b32_dpp v189, v165 row_shr:1 row_mask:0xf bank_mask:0xf bound_ctrl:1
	v_cndmask_b32_e64 v167, v167, 0, s[4:5]
	v_cndmask_b32_e64 v166, v166, 0, s[4:5]
	v_pk_fma_f32 v[166:167], v[132:133], v[166:167], v[144:145]
	v_cndmask_b32_e64 v239, v189, 0, s[2:3]
	v_cndmask_b32_e64 v238, v187, 0, s[2:3]
	v_pk_fma_f32 v[166:167], v[136:137], v[238:239], v[166:167]
	s_nop 0
	v_pk_fma_f32 v[166:167], v[140:141], v[164:165], v[166:167]
	s_nop 0
	v_mul_f32_e32 v187, 0x3d372713, v166
	v_mul_f32_e32 v187, v166, v187
	v_fma_f32 v187, v166, v187, v166
	v_mul_f32_e32 v187, 0xbfcc422a, v187
	v_mul_f32_e32 v187, 0x3fb8aa3b, v187
	v_exp_f32_e32 v187, v187
	s_nop 0
	v_add_f32_e32 v187, 1.0, v187
	v_rcp_f32_e32 v238, v187
	v_mul_f32_e32 v187, 0x3d372713, v167
	v_mul_f32_e32 v187, v167, v187
	v_fma_f32 v187, v167, v187, v167
	v_mul_f32_e32 v187, 0xbfcc422a, v187
	v_mul_f32_e32 v187, 0x3fb8aa3b, v187
	v_exp_f32_e32 v187, v187
	s_nop 0
	v_add_f32_e32 v187, 1.0, v187
	v_rcp_f32_e32 v239, v187
	s_nop 0
	v_pk_mul_f32 v[166:167], v[166:167], v[238:239]
	s_nop 0
	v_pk_mul_f32 v[242:243], v[228:229], v[166:167]
	v_pk_mul_f32 v[166:167], v[126:127], v[96:97] op_sel_hi:[1,0]
	s_nop 1
	v_mov_b32_dpp v187, v166 row_shr:2 row_mask:0xf bank_mask:0xf bound_ctrl:1
	v_mov_b32_dpp v191, v167 row_shr:2 row_mask:0xf bank_mask:0xf bound_ctrl:1
	v_mov_b32_dpp v96, v166 row_shr:1 row_mask:0xf bank_mask:0xf bound_ctrl:1
	v_mov_b32_dpp v189, v167 row_shr:1 row_mask:0xf bank_mask:0xf bound_ctrl:1
	v_cndmask_b32_e64 v245, v191, 0, s[4:5]
	v_cndmask_b32_e64 v244, v187, 0, s[4:5]
	v_cndmask_b32_e64 v239, v189, 0, s[2:3]
	v_cndmask_b32_e64 v238, v96, 0, s[2:3]
	v_pk_fma_f32 v[244:245], v[134:135], v[244:245], v[146:147]
	s_nop 0
	v_pk_fma_f32 v[238:239], v[138:139], v[238:239], v[244:245]
	s_nop 0
	v_pk_fma_f32 v[238:239], v[142:143], v[166:167], v[238:239]
	s_nop 0
	v_mul_f32_e32 v96, 0x3d372713, v238
	v_mul_f32_e32 v96, v238, v96
	v_fma_f32 v96, v238, v96, v238
	v_mul_f32_e32 v96, 0xbfcc422a, v96
	v_mul_f32_e32 v96, 0x3fb8aa3b, v96
	v_exp_f32_e32 v96, v96
	s_nop 0
	v_add_f32_e32 v96, 1.0, v96
	v_rcp_f32_e32 v244, v96
	v_mul_f32_e32 v96, 0x3d372713, v239
	v_mul_f32_e32 v96, v239, v96
	v_fma_f32 v96, v239, v96, v239
	v_mul_f32_e32 v96, 0xbfcc422a, v96
	v_mul_f32_e32 v96, 0x3fb8aa3b, v96
	v_exp_f32_e32 v96, v96
	s_nop 0
	v_add_f32_e32 v96, 1.0, v96
	v_rcp_f32_e32 v245, v96
	v_mul_hi_i32 v96, v212, s10
	v_lshrrev_b32_e32 v187, 31, v96
	v_ashrrev_i32_e32 v96, 7, v96
	v_pk_mul_f32 v[238:239], v[238:239], v[244:245]
	s_movk_i32 s10, 0x203d
	v_pk_mul_f32 v[244:245], v[230:231], v[238:239]
	v_cvt_pk_bf16_f32 v238, v232, v233
	v_mov_b64_e32 v[232:233], s[22:23]
	v_mad_i64_i32 v[232:233], s[8:9], v212, s43, v[232:233]
	v_cvt_pk_bf16_f32 v239, v240, v241
	v_cvt_pk_bf16_f32 v240, v242, v243
	v_cvt_pk_bf16_f32 v241, v244, v245
	v_lshl_add_u64 v[232:233], v[98:99], 1, v[232:233]
	global_store_dwordx4 v[232:233], v[238:241], off
	v_add_u32_e32 v232, v96, v187
	v_mul_i32_i24_e32 v96, 0x810, v232
	v_cmp_gt_i32_e64 s[8:9], s73, v212
	v_sub_u32_e32 v96, v212, v96
	v_cmp_lt_i32_e32 vcc, s10, v212
	v_cndmask_b32_e64 v187, 0, v96, s[8:9]
	v_cmp_gt_i32_e64 s[10:11], 2, v187
	s_or_b64 s[10:11], vcc, s[10:11]
	s_or_b64 s[78:79], s[4:5], s[10:11]
	s_and_saveexec_b64 s[10:11], s[78:79]
	s_cbranch_execz .LBB0_1918
	v_mad_i64_i32 v[212:213], s[78:79], v212, s43, 0
	v_lshl_add_u64 v[212:213], v[212:213], 1, s[20:21]
	v_cvt_pk_bf16_f32 v238, v168, v169
	v_cvt_pk_bf16_f32 v239, v170, v171
	v_cvt_pk_bf16_f32 v240, v164, v165
	v_cvt_pk_bf16_f32 v241, v166, v167
	v_lshl_add_u64 v[212:213], v[98:99], 1, v[212:213]
	global_store_dwordx4 v[212:213], v[238:241], off
	v_add_co_u32_e32 v212, vcc, 0x2000, v212
	v_cvt_pk_bf16_f32 v242, v222, v223
	v_cvt_pk_bf16_f32 v243, v226, v227
	v_cvt_pk_bf16_f32 v244, v228, v229
	v_cvt_pk_bf16_f32 v245, v230, v231
	v_addc_co_u32_e32 v213, vcc, 0, v213, vcc
	global_store_dwordx4 v[212:213], v[242:245], off offset:2816
